# kernel-start cooperative grid.sync skipped (phase 0 has no cross-workgroup dependency; the first XCD barrier completes the census itself)
# baseline (speedup 1.0000x reference)
.LBB0_5:
	s_or_b64 exec, exec, s[4:5]
	s_load_dwordx16 s[36:51], s[0:1], 0x80
	s_cmp_eq_u64 s[90:91], 0
	s_waitcnt lgkmcnt(0)
	v_writelane_b32 v230, s36, 18
	s_nop 1
	v_writelane_b32 v230, s37, 19
	v_writelane_b32 v230, s38, 20
	v_writelane_b32 v230, s39, 21
	v_writelane_b32 v230, s40, 22
	v_writelane_b32 v230, s41, 23
	v_writelane_b32 v230, s42, 24
	v_writelane_b32 v230, s43, 25
	v_writelane_b32 v230, s44, 26
	v_writelane_b32 v230, s45, 27
	v_writelane_b32 v230, s46, 28
	v_writelane_b32 v230, s47, 29
	v_writelane_b32 v230, s48, 30
	v_writelane_b32 v230, s49, 31
	v_writelane_b32 v230, s50, 32
	v_writelane_b32 v230, s51, 33
	s_branch .LBB0_17
	v_lshrrev_b32_e32 v1, 20, v0
	v_lshrrev_b32_e32 v0, 10, v0
	v_or_b32_e32 v0, v0, v1
	s_movk_i32 s3, 0x3ff
	v_and_or_b32 v0, v0, s3, v194
	v_cmp_eq_u32_e32 vcc, 0, v0
	s_barrier
	s_and_saveexec_b64 s[4:5], vcc
	s_cbranch_execz .LBB0_16
	buffer_wbl2 sc1
	s_waitcnt vmcnt(0)
	s_load_dwordx2 s[6:7], s[6:7], 0x58
	v_mov_b32_e32 v2, 0
	s_mov_b64 s[36:37], exec
	v_mbcnt_lo_u32_b32 v1, s36, 0
	v_mbcnt_hi_u32_b32 v1, s37, v1
	s_waitcnt lgkmcnt(0)
	global_load_dword v0, v2, s[6:7] offset:40
	v_cmp_eq_u32_e32 vcc, 0, v1
	s_and_saveexec_b64 s[38:39], vcc
	s_cbranch_execz .LBB0_9
	s_bcnt1_i32_b64 s3, s[36:37]
	v_mov_b32_e32 v3, s3
	global_atomic_add v3, v2, v3, s[6:7] offset:32 sc0
